# stack28 + weight-conversion scaled paths (P0 W_gu/W_in, P6 FFN2 W_gu): 8 row loads + 8 scale loads issued together, counted waits (was 16 dependent round trips per unit)
# baseline (speedup 1.0000x reference)
.LBB0_31:
	s_add_u32 s34, s34, 0xc0400
	s_addc_u32 s35, s35, 0
	v_add_u32_e32 v12, 0x2080, v12
	v_lshl_add_u64 v[32:33], v[32:33], 0, s[28:29]
	s_cmp_lg_u32 s34, 0x180800
	s_cbranch_scc0 .LBB0_48
.LBB0_32:
	v_lshl_add_u64 v[0:1], v[28:29], 0, s[34:35]
	global_load_dwordx4 v[118:121], v[0:1], off
	v_lshl_add_u64 v[4:5], v[42:43], 0, s[34:35]
	global_load_dwordx4 v[122:125], v[4:5], off
	v_lshl_add_u64 v[0:1], v[40:41], 0, s[34:35]
	global_load_dwordx4 v[126:129], v[0:1], off
	v_lshl_add_u64 v[4:5], v[38:39], 0, s[34:35]
	global_load_dwordx4 v[130:133], v[4:5], off
	v_lshl_add_u64 v[0:1], v[36:37], 0, s[34:35]
	global_load_dwordx4 v[134:137], v[0:1], off
	v_lshl_add_u64 v[4:5], v[34:35], 0, s[34:35]
	global_load_dwordx4 v[138:141], v[4:5], off
	v_lshl_add_u64 v[0:1], v[30:31], 0, s[34:35]
	global_load_dwordx4 v[142:145], v[0:1], off
	v_lshl_add_u64 v[4:5], v[26:27], 0, s[34:35]
	global_load_dwordx4 v[146:149], v[4:5], off
	v_cndmask_b32_e64 v4, 0, 1, s[36:37]
	v_cmp_ne_u32_e64 s[2:3], 1, v4
	s_andn2_b64 vcc, exec, s[36:37]
	s_cbranch_vccnz .LcvwC_ns
	global_load_dword v150, v[32:33], off offset:-112
	global_load_dword v152, v[32:33], off offset:-96
	global_load_dword v154, v[32:33], off offset:-80
	global_load_dword v156, v[32:33], off offset:-64
	global_load_dword v158, v[32:33], off offset:-48
	global_load_dword v160, v[32:33], off offset:-32
	global_load_dword v162, v[32:33], off offset:-16
	global_load_dword v164, v[32:33], off
	s_waitcnt vmcnt(7)
	v_pk_mul_f32 v[120:121], v[120:121], v[150:151] op_sel_hi:[1,0]
	v_pk_mul_f32 v[118:119], v[118:119], v[150:151] op_sel_hi:[1,0]
	ds_write2_b32 v12, v118, v119 offset1:1
	ds_write2_b32 v12, v120, v121 offset0:2 offset1:3
	s_waitcnt vmcnt(6)
	v_pk_mul_f32 v[124:125], v[124:125], v[152:153] op_sel_hi:[1,0]
	v_pk_mul_f32 v[122:123], v[122:123], v[152:153] op_sel_hi:[1,0]
	v_add_u32_e32 v80, 0x410, v12
	ds_write2_b32 v80, v122, v123 offset1:1
	v_add_u32_e32 v4, 0x418, v12
	ds_write2_b32 v4, v124, v125 offset1:1
	s_waitcnt vmcnt(5)
	v_pk_mul_f32 v[128:129], v[128:129], v[154:155] op_sel_hi:[1,0]
	v_pk_mul_f32 v[126:127], v[126:127], v[154:155] op_sel_hi:[1,0]
	v_add_u32_e32 v80, 0x820, v12
	ds_write2_b32 v80, v126, v127 offset1:1
	v_add_u32_e32 v4, 0x828, v12
	ds_write2_b32 v4, v128, v129 offset1:1
	s_waitcnt vmcnt(4)
	v_pk_mul_f32 v[132:133], v[132:133], v[156:157] op_sel_hi:[1,0]
	v_pk_mul_f32 v[130:131], v[130:131], v[156:157] op_sel_hi:[1,0]
	v_add_u32_e32 v80, 0xc30, v12
	ds_write2_b32 v80, v130, v131 offset1:1
	v_add_u32_e32 v4, 0xc38, v12
	ds_write2_b32 v4, v132, v133 offset1:1
	s_waitcnt vmcnt(3)
	v_pk_mul_f32 v[136:137], v[136:137], v[158:159] op_sel_hi:[1,0]
	v_pk_mul_f32 v[134:135], v[134:135], v[158:159] op_sel_hi:[1,0]
	v_add_u32_e32 v80, 0x1040, v12
	ds_write2_b32 v80, v134, v135 offset1:1
	v_add_u32_e32 v4, 0x1048, v12
	ds_write2_b32 v4, v136, v137 offset1:1
	s_waitcnt vmcnt(2)
	v_pk_mul_f32 v[140:141], v[140:141], v[160:161] op_sel_hi:[1,0]
	v_pk_mul_f32 v[138:139], v[138:139], v[160:161] op_sel_hi:[1,0]
	v_add_u32_e32 v80, 0x1450, v12
	ds_write2_b32 v80, v138, v139 offset1:1
	v_add_u32_e32 v4, 0x1458, v12
	ds_write2_b32 v4, v140, v141 offset1:1
	s_waitcnt vmcnt(1)
	v_pk_mul_f32 v[144:145], v[144:145], v[162:163] op_sel_hi:[1,0]
	v_pk_mul_f32 v[142:143], v[142:143], v[162:163] op_sel_hi:[1,0]
	v_add_u32_e32 v80, 0x1860, v12
	ds_write2_b32 v80, v142, v143 offset1:1
	v_add_u32_e32 v4, 0x1868, v12
	ds_write2_b32 v4, v144, v145 offset1:1
	s_waitcnt vmcnt(0)
	v_pk_mul_f32 v[148:149], v[148:149], v[164:165] op_sel_hi:[1,0]
	v_pk_mul_f32 v[146:147], v[146:147], v[164:165] op_sel_hi:[1,0]
	v_add_u32_e32 v80, 0x1c70, v12
	ds_write2_b32 v80, v146, v147 offset1:1
	v_add_u32_e32 v4, 0x1c78, v12
	ds_write2_b32 v4, v148, v149 offset1:1
	s_branch .LBB0_31
.LcvwC_ns:
	s_waitcnt vmcnt(7)
	ds_write2_b32 v12, v118, v119 offset1:1
	ds_write2_b32 v12, v120, v121 offset0:2 offset1:3
	s_waitcnt vmcnt(6)
	v_add_u32_e32 v80, 0x410, v12
	ds_write2_b32 v80, v122, v123 offset1:1
	v_add_u32_e32 v4, 0x418, v12
	ds_write2_b32 v4, v124, v125 offset1:1
	s_waitcnt vmcnt(5)
	v_add_u32_e32 v80, 0x820, v12
	ds_write2_b32 v80, v126, v127 offset1:1
	v_add_u32_e32 v4, 0x828, v12
	ds_write2_b32 v4, v128, v129 offset1:1
	s_waitcnt vmcnt(4)
	v_add_u32_e32 v80, 0xc30, v12
	ds_write2_b32 v80, v130, v131 offset1:1
	v_add_u32_e32 v4, 0xc38, v12
	ds_write2_b32 v4, v132, v133 offset1:1
	s_waitcnt vmcnt(3)
	v_add_u32_e32 v80, 0x1040, v12
	ds_write2_b32 v80, v134, v135 offset1:1
	v_add_u32_e32 v4, 0x1048, v12
	ds_write2_b32 v4, v136, v137 offset1:1
	s_waitcnt vmcnt(2)
	v_add_u32_e32 v80, 0x1450, v12
	ds_write2_b32 v80, v138, v139 offset1:1
	v_add_u32_e32 v4, 0x1458, v12
	ds_write2_b32 v4, v140, v141 offset1:1
	s_waitcnt vmcnt(1)
	v_add_u32_e32 v80, 0x1860, v12
	ds_write2_b32 v80, v142, v143 offset1:1
	v_add_u32_e32 v4, 0x1868, v12
	ds_write2_b32 v4, v144, v145 offset1:1
	s_waitcnt vmcnt(0)
	v_add_u32_e32 v80, 0x1c70, v12
	ds_write2_b32 v80, v146, v147 offset1:1
	v_add_u32_e32 v4, 0x1c78, v12
	ds_write2_b32 v4, v148, v149 offset1:1
	s_branch .LBB0_31

.LBB0_57:
	v_add_u32_e32 v12, 0x2080, v12
	s_add_i32 s24, s24, 32
	v_lshl_add_u64 v[30:31], v[30:31], 0, s[28:29]
	s_cmp_lg_u32 s24, 64
	s_cbranch_scc0 .LBB0_22
.LBB0_58:
	v_add_u32_e32 v32, s24, v28
	v_ashrrev_i32_e32 v33, 31, v32
	v_mad_i64_i32 v[0:1], s[42:43], v32, s26, v[26:27]
	global_load_dwordx4 v[118:121], v[0:1], off
	v_add_u32_e32 v4, 4, v32
	v_mad_i64_i32 v[4:5], s[42:43], v4, s26, v[26:27]
	global_load_dwordx4 v[122:125], v[4:5], off
	v_add_u32_e32 v0, 8, v32
	v_mad_i64_i32 v[0:1], s[42:43], v0, s26, v[26:27]
	global_load_dwordx4 v[126:129], v[0:1], off
	v_add_u32_e32 v4, 12, v32
	v_mad_i64_i32 v[4:5], s[42:43], v4, s26, v[26:27]
	global_load_dwordx4 v[130:133], v[4:5], off
	v_add_u32_e32 v0, 16, v32
	v_mad_i64_i32 v[0:1], s[42:43], v0, s26, v[26:27]
	global_load_dwordx4 v[134:137], v[0:1], off
	v_add_u32_e32 v4, 20, v32
	v_mad_i64_i32 v[4:5], s[42:43], v4, s26, v[26:27]
	global_load_dwordx4 v[138:141], v[4:5], off
	v_add_u32_e32 v0, 24, v32
	v_mad_i64_i32 v[0:1], s[42:43], v0, s26, v[26:27]
	global_load_dwordx4 v[142:145], v[0:1], off
	v_add_u32_e32 v4, 28, v32
	v_mad_i64_i32 v[4:5], s[42:43], v4, s26, v[26:27]
	global_load_dwordx4 v[146:149], v[4:5], off
	v_cndmask_b32_e64 v4, 0, 1, s[36:37]
	v_cmp_ne_u32_e64 s[2:3], 1, v4
	s_andn2_b64 vcc, exec, s[36:37]
	s_cbranch_vccnz .LcvwA_ns
	v_lshl_add_u64 v[4:5], v[32:33], 2, s[4:5]
	global_load_dword v150, v[4:5], off
	global_load_dword v152, v[30:31], off offset:-96
	global_load_dword v154, v[30:31], off offset:-80
	global_load_dword v156, v[30:31], off offset:-64
	global_load_dword v158, v[30:31], off offset:-48
	global_load_dword v160, v[30:31], off offset:-32
	global_load_dword v162, v[30:31], off offset:-16
	global_load_dword v164, v[30:31], off
	s_waitcnt vmcnt(7)
	v_pk_mul_f32 v[120:121], v[120:121], v[150:151] op_sel_hi:[1,0]
	v_pk_mul_f32 v[118:119], v[118:119], v[150:151] op_sel_hi:[1,0]
	ds_write2_b32 v12, v118, v119 offset1:1
	ds_write2_b32 v12, v120, v121 offset0:2 offset1:3
	s_waitcnt vmcnt(6)
	v_pk_mul_f32 v[124:125], v[124:125], v[152:153] op_sel_hi:[1,0]
	v_pk_mul_f32 v[122:123], v[122:123], v[152:153] op_sel_hi:[1,0]
	v_add_u32_e32 v29, 0x410, v12
	ds_write2_b32 v29, v122, v123 offset1:1
	v_add_u32_e32 v4, 0x418, v12
	ds_write2_b32 v4, v124, v125 offset1:1
	s_waitcnt vmcnt(5)
	v_pk_mul_f32 v[128:129], v[128:129], v[154:155] op_sel_hi:[1,0]
	v_pk_mul_f32 v[126:127], v[126:127], v[154:155] op_sel_hi:[1,0]
	v_add_u32_e32 v29, 0x820, v12
	ds_write2_b32 v29, v126, v127 offset1:1
	v_add_u32_e32 v4, 0x828, v12
	ds_write2_b32 v4, v128, v129 offset1:1
	s_waitcnt vmcnt(4)
	v_pk_mul_f32 v[132:133], v[132:133], v[156:157] op_sel_hi:[1,0]
	v_pk_mul_f32 v[130:131], v[130:131], v[156:157] op_sel_hi:[1,0]
	v_add_u32_e32 v29, 0xc30, v12
	ds_write2_b32 v29, v130, v131 offset1:1
	v_add_u32_e32 v4, 0xc38, v12
	ds_write2_b32 v4, v132, v133 offset1:1
	s_waitcnt vmcnt(3)
	v_pk_mul_f32 v[136:137], v[136:137], v[158:159] op_sel_hi:[1,0]
	v_pk_mul_f32 v[134:135], v[134:135], v[158:159] op_sel_hi:[1,0]
	v_add_u32_e32 v29, 0x1040, v12
	ds_write2_b32 v29, v134, v135 offset1:1
	v_add_u32_e32 v4, 0x1048, v12
	ds_write2_b32 v4, v136, v137 offset1:1
	s_waitcnt vmcnt(2)
	v_pk_mul_f32 v[140:141], v[140:141], v[160:161] op_sel_hi:[1,0]
	v_pk_mul_f32 v[138:139], v[138:139], v[160:161] op_sel_hi:[1,0]
	v_add_u32_e32 v29, 0x1450, v12
	ds_write2_b32 v29, v138, v139 offset1:1
	v_add_u32_e32 v4, 0x1458, v12
	ds_write2_b32 v4, v140, v141 offset1:1
	s_waitcnt vmcnt(1)
	v_pk_mul_f32 v[144:145], v[144:145], v[162:163] op_sel_hi:[1,0]
	v_pk_mul_f32 v[142:143], v[142:143], v[162:163] op_sel_hi:[1,0]
	v_add_u32_e32 v29, 0x1860, v12
	ds_write2_b32 v29, v142, v143 offset1:1
	v_add_u32_e32 v4, 0x1868, v12
	ds_write2_b32 v4, v144, v145 offset1:1
	s_waitcnt vmcnt(0)
	v_pk_mul_f32 v[148:149], v[148:149], v[164:165] op_sel_hi:[1,0]
	v_pk_mul_f32 v[146:147], v[146:147], v[164:165] op_sel_hi:[1,0]
	v_add_u32_e32 v29, 0x1c70, v12
	ds_write2_b32 v29, v146, v147 offset1:1
	v_add_u32_e32 v4, 0x1c78, v12
	ds_write2_b32 v4, v148, v149 offset1:1
	s_branch .LBB0_57
.LcvwA_ns:
	s_waitcnt vmcnt(7)
	ds_write2_b32 v12, v118, v119 offset1:1
	ds_write2_b32 v12, v120, v121 offset0:2 offset1:3
	s_waitcnt vmcnt(6)
	v_add_u32_e32 v29, 0x410, v12
	ds_write2_b32 v29, v122, v123 offset1:1
	v_add_u32_e32 v4, 0x418, v12
	ds_write2_b32 v4, v124, v125 offset1:1
	s_waitcnt vmcnt(5)
	v_add_u32_e32 v29, 0x820, v12
	ds_write2_b32 v29, v126, v127 offset1:1
	v_add_u32_e32 v4, 0x828, v12
	ds_write2_b32 v4, v128, v129 offset1:1
	s_waitcnt vmcnt(4)
	v_add_u32_e32 v29, 0xc30, v12
	ds_write2_b32 v29, v130, v131 offset1:1
	v_add_u32_e32 v4, 0xc38, v12
	ds_write2_b32 v4, v132, v133 offset1:1
	s_waitcnt vmcnt(3)
	v_add_u32_e32 v29, 0x1040, v12
	ds_write2_b32 v29, v134, v135 offset1:1
	v_add_u32_e32 v4, 0x1048, v12
	ds_write2_b32 v4, v136, v137 offset1:1
	s_waitcnt vmcnt(2)
	v_add_u32_e32 v29, 0x1450, v12
	ds_write2_b32 v29, v138, v139 offset1:1
	v_add_u32_e32 v4, 0x1458, v12
	ds_write2_b32 v4, v140, v141 offset1:1
	s_waitcnt vmcnt(1)
	v_add_u32_e32 v29, 0x1860, v12
	ds_write2_b32 v29, v142, v143 offset1:1
	v_add_u32_e32 v4, 0x1868, v12
	ds_write2_b32 v4, v144, v145 offset1:1
	s_waitcnt vmcnt(0)
	v_add_u32_e32 v29, 0x1c70, v12
	ds_write2_b32 v29, v146, v147 offset1:1
	v_add_u32_e32 v4, 0x1c78, v12
	ds_write2_b32 v4, v148, v149 offset1:1
	s_branch .LBB0_57

.LBB0_962:
	v_add_u32_e32 v10, 0x2080, v10
	s_add_i32 s34, s34, 32
	v_lshl_add_u64 v[20:21], v[20:21], 0, s[14:15]
	s_cmp_lg_u32 s34, 64
	s_cbranch_scc0 .LBB0_954
.LBB0_963:
	v_add_u32_e32 v22, s34, v18
	v_ashrrev_i32_e32 v23, 31, v22
	v_mad_i64_i32 v[0:1], s[36:37], v22, s27, v[16:17]
	global_load_dwordx4 v[140:143], v[0:1], off
	v_add_u32_e32 v4, 4, v22
	v_mad_i64_i32 v[4:5], s[36:37], v4, s27, v[16:17]
	global_load_dwordx4 v[144:147], v[4:5], off
	v_add_u32_e32 v0, 8, v22
	v_mad_i64_i32 v[0:1], s[36:37], v0, s27, v[16:17]
	global_load_dwordx4 v[148:151], v[0:1], off
	v_add_u32_e32 v4, 12, v22
	v_mad_i64_i32 v[4:5], s[36:37], v4, s27, v[16:17]
	global_load_dwordx4 v[152:155], v[4:5], off
	v_add_u32_e32 v0, 16, v22
	v_mad_i64_i32 v[0:1], s[36:37], v0, s27, v[16:17]
	global_load_dwordx4 v[156:159], v[0:1], off
	v_add_u32_e32 v4, 20, v22
	v_mad_i64_i32 v[4:5], s[36:37], v4, s27, v[16:17]
	global_load_dwordx4 v[160:163], v[4:5], off
	v_add_u32_e32 v0, 24, v22
	v_mad_i64_i32 v[0:1], s[36:37], v0, s27, v[16:17]
	global_load_dwordx4 v[164:167], v[0:1], off
	v_add_u32_e32 v4, 28, v22
	v_mad_i64_i32 v[4:5], s[36:37], v4, s27, v[16:17]
	global_load_dwordx4 v[168:171], v[4:5], off
	v_cndmask_b32_e64 v4, 0, 1, s[8:9]
	v_cmp_ne_u32_e64 s[2:3], 1, v4
	s_andn2_b64 vcc, exec, s[8:9]
	s_cbranch_vccnz .LcvwB_ns
	v_lshl_add_u64 v[4:5], v[22:23], 2, s[6:7]
	global_load_dword v172, v[4:5], off
	global_load_dword v174, v[20:21], off offset:-96
	global_load_dword v176, v[20:21], off offset:-80
	global_load_dword v178, v[20:21], off offset:-64
	global_load_dword v180, v[20:21], off offset:-48
	global_load_dword v182, v[20:21], off offset:-32
	global_load_dword v184, v[20:21], off offset:-16
	global_load_dword v186, v[20:21], off
	s_waitcnt vmcnt(7)
	v_pk_mul_f32 v[142:143], v[142:143], v[172:173] op_sel_hi:[1,0]
	v_pk_mul_f32 v[140:141], v[140:141], v[172:173] op_sel_hi:[1,0]
	ds_write2_b32 v10, v140, v141 offset1:1
	ds_write2_b32 v10, v142, v143 offset0:2 offset1:3
	s_waitcnt vmcnt(6)
	v_pk_mul_f32 v[146:147], v[146:147], v[174:175] op_sel_hi:[1,0]
	v_pk_mul_f32 v[144:145], v[144:145], v[174:175] op_sel_hi:[1,0]
	v_add_u32_e32 v19, 0x410, v10
	ds_write2_b32 v19, v144, v145 offset1:1
	v_add_u32_e32 v4, 0x418, v10
	ds_write2_b32 v4, v146, v147 offset1:1
	s_waitcnt vmcnt(5)
	v_pk_mul_f32 v[150:151], v[150:151], v[176:177] op_sel_hi:[1,0]
	v_pk_mul_f32 v[148:149], v[148:149], v[176:177] op_sel_hi:[1,0]
	v_add_u32_e32 v19, 0x820, v10
	ds_write2_b32 v19, v148, v149 offset1:1
	v_add_u32_e32 v4, 0x828, v10
	ds_write2_b32 v4, v150, v151 offset1:1
	s_waitcnt vmcnt(4)
	v_pk_mul_f32 v[154:155], v[154:155], v[178:179] op_sel_hi:[1,0]
	v_pk_mul_f32 v[152:153], v[152:153], v[178:179] op_sel_hi:[1,0]
	v_add_u32_e32 v19, 0xc30, v10
	ds_write2_b32 v19, v152, v153 offset1:1
	v_add_u32_e32 v4, 0xc38, v10
	ds_write2_b32 v4, v154, v155 offset1:1
	s_waitcnt vmcnt(3)
	v_pk_mul_f32 v[158:159], v[158:159], v[180:181] op_sel_hi:[1,0]
	v_pk_mul_f32 v[156:157], v[156:157], v[180:181] op_sel_hi:[1,0]
	v_add_u32_e32 v19, 0x1040, v10
	ds_write2_b32 v19, v156, v157 offset1:1
	v_add_u32_e32 v4, 0x1048, v10
	ds_write2_b32 v4, v158, v159 offset1:1
	s_waitcnt vmcnt(2)
	v_pk_mul_f32 v[162:163], v[162:163], v[182:183] op_sel_hi:[1,0]
	v_pk_mul_f32 v[160:161], v[160:161], v[182:183] op_sel_hi:[1,0]
	v_add_u32_e32 v19, 0x1450, v10
	ds_write2_b32 v19, v160, v161 offset1:1
	v_add_u32_e32 v4, 0x1458, v10
	ds_write2_b32 v4, v162, v163 offset1:1
	s_waitcnt vmcnt(1)
	v_pk_mul_f32 v[166:167], v[166:167], v[184:185] op_sel_hi:[1,0]
	v_pk_mul_f32 v[164:165], v[164:165], v[184:185] op_sel_hi:[1,0]
	v_add_u32_e32 v19, 0x1860, v10
	ds_write2_b32 v19, v164, v165 offset1:1
	v_add_u32_e32 v4, 0x1868, v10
	ds_write2_b32 v4, v166, v167 offset1:1
	s_waitcnt vmcnt(0)
	v_pk_mul_f32 v[170:171], v[170:171], v[186:187] op_sel_hi:[1,0]
	v_pk_mul_f32 v[168:169], v[168:169], v[186:187] op_sel_hi:[1,0]
	v_add_u32_e32 v19, 0x1c70, v10
	ds_write2_b32 v19, v168, v169 offset1:1
	v_add_u32_e32 v4, 0x1c78, v10
	ds_write2_b32 v4, v170, v171 offset1:1
	s_branch .LBB0_962
.LcvwB_ns:
	s_waitcnt vmcnt(7)
	ds_write2_b32 v10, v140, v141 offset1:1
	ds_write2_b32 v10, v142, v143 offset0:2 offset1:3
	s_waitcnt vmcnt(6)
	v_add_u32_e32 v19, 0x410, v10
	ds_write2_b32 v19, v144, v145 offset1:1
	v_add_u32_e32 v4, 0x418, v10
	ds_write2_b32 v4, v146, v147 offset1:1
	s_waitcnt vmcnt(5)
	v_add_u32_e32 v19, 0x820, v10
	ds_write2_b32 v19, v148, v149 offset1:1
	v_add_u32_e32 v4, 0x828, v10
	ds_write2_b32 v4, v150, v151 offset1:1
	s_waitcnt vmcnt(4)
	v_add_u32_e32 v19, 0xc30, v10
	ds_write2_b32 v19, v152, v153 offset1:1
	v_add_u32_e32 v4, 0xc38, v10
	ds_write2_b32 v4, v154, v155 offset1:1
	s_waitcnt vmcnt(3)
	v_add_u32_e32 v19, 0x1040, v10
	ds_write2_b32 v19, v156, v157 offset1:1
	v_add_u32_e32 v4, 0x1048, v10
	ds_write2_b32 v4, v158, v159 offset1:1
	s_waitcnt vmcnt(2)
	v_add_u32_e32 v19, 0x1450, v10
	ds_write2_b32 v19, v160, v161 offset1:1
	v_add_u32_e32 v4, 0x1458, v10
	ds_write2_b32 v4, v162, v163 offset1:1
	s_waitcnt vmcnt(1)
	v_add_u32_e32 v19, 0x1860, v10
	ds_write2_b32 v19, v164, v165 offset1:1
	v_add_u32_e32 v4, 0x1868, v10
	ds_write2_b32 v4, v166, v167 offset1:1
	s_waitcnt vmcnt(0)
	v_add_u32_e32 v19, 0x1c70, v10
	ds_write2_b32 v19, v168, v169 offset1:1
	v_add_u32_e32 v4, 0x1c78, v10
	ds_write2_b32 v4, v170, v171 offset1:1
	s_branch .LBB0_962
